# v22 + no s_nop 4 in attention LDS-DMA blocks + seam leader publishes the generation before its own L1 invalidate
# baseline (speedup 1.0000x reference)
.LBB0_478:
	s_or_b64 exec, exec, s[6:7]
	s_mov_b64 s[6:7], exec
	v_mbcnt_lo_u32_b32 v2, s6, 0
	v_mbcnt_hi_u32_b32 v2, s7, v2
	v_cmp_eq_u32_e32 vcc, 0, v2
	s_waitcnt vmcnt(0)
	s_and_saveexec_b64 s[8:9], vcc
	s_cbranch_execz .LBB0_480
	s_bcnt1_i32_b64 s3, s[6:7]
	v_mov_b32_e32 v2, 0x2000
	v_mov_b32_e32 v3, s3
	global_atomic_add v2, v3, s[4:5] offset:1024
.LBB0_480:
	s_or_b64 exec, exec, s[8:9]
	buffer_inv sc1
	s_waitcnt vmcnt(0)

.LBB0_560:
	s_mov_b64 s[0:1], exec
	s_waitcnt lgkmcnt(0)
	v_mbcnt_lo_u32_b32 v2, s0, 0
	v_mbcnt_hi_u32_b32 v2, s1, v2
	v_cmp_eq_u32_e32 vcc, 0, v2
	s_waitcnt vmcnt(0)
	s_and_saveexec_b64 s[8:9], vcc
	s_cbranch_execz .LBB0_562
	s_bcnt1_i32_b64 s0, s[0:1]
	v_mov_b32_e32 v2, 0x2000
	v_mov_b32_e32 v3, s0
	global_atomic_add v2, v3, s[6:7] offset:1024

.LBB0_666:
	s_mov_b64 s[0:1], exec
	s_waitcnt lgkmcnt(0)
	v_mbcnt_lo_u32_b32 v2, s0, 0
	v_mbcnt_hi_u32_b32 v2, s1, v2
	v_cmp_eq_u32_e32 vcc, 0, v2
	s_waitcnt vmcnt(0)
	s_and_saveexec_b64 s[10:11], vcc
	s_cbranch_execz .LBB0_668
	s_bcnt1_i32_b64 s0, s[0:1]
	v_mov_b32_e32 v2, 0x2000
	v_mov_b32_e32 v3, s0
	global_atomic_add v2, v3, s[8:9] offset:1024
.LBB0_668:
	s_or_b64 exec, exec, s[10:11]
	buffer_inv sc1
	s_waitcnt vmcnt(0)

.LBB0_1293:
	s_mov_b64 s[0:1], exec
	s_waitcnt lgkmcnt(0)
	v_mbcnt_lo_u32_b32 v1, s0, 0
	v_mbcnt_hi_u32_b32 v1, s1, v1
	v_cmp_eq_u32_e32 vcc, 0, v1
	s_waitcnt vmcnt(0)
	s_and_saveexec_b64 s[8:9], vcc
	s_cbranch_execz .LBB0_1295
	s_bcnt1_i32_b64 s0, s[0:1]
	v_mov_b32_e32 v1, 0x2000
	v_mov_b32_e32 v2, s0
	global_atomic_add v1, v2, s[6:7] offset:1024

.LBB0_1349:
	s_add_i32 s67, s0, 0xffffffa0
	s_cmp_gt_u32 s67, 0xffffff00
	s_cselect_b64 s[86:87], -1, 0
	s_cmpk_gt_i32 s0, 0xff60
	s_mov_b64 s[88:89], -1
	v_add_u32_e32 v214, v189, v199
	v_add_u32_e32 v213, v189, v203
	s_cbranch_scc0 .LBB0_1369
	ds_read_b128 v[34:37], v214
	ds_read_b128 v[106:109], v214 offset:2048
	ds_read_b128 v[102:105], v213
	ds_read_b128 v[98:101], v213 offset:2048
	ds_read_b128 v[94:97], v214 offset:4096
	ds_read_b128 v[90:93], v214 offset:6144
	ds_read_b128 v[86:89], v213 offset:4096
	ds_read_b128 v[82:85], v213 offset:6144
	s_add_i32 s67, s82, 1
	s_cmp_ge_i32 s67, s39
	s_cbranch_scc0 .LBB0_1354
	s_andn2_b64 vcc, exec, s[70:71]
	s_cbranch_vccnz .LBB0_1353
	s_xor_b32 s83, s96, 1
	s_mul_i32 s88, s83, 0x3000
	s_add_i32 s88, s88, s93
	s_mov_b32 s89, m0
	s_mov_b32 m0, s88
	s_nop 0
	global_load_lds_dwordx4 v1, s[74:75]
	s_mov_b32 m0, s89
	s_lshl_b32 s83, s83, 13
	s_add_i32 s83, s83, s94
	s_mov_b32 s88, m0
	s_mov_b32 m0, s83
	s_nop 0
	global_load_lds_dwordx4 v196, s[76:77]
	s_mov_b32 m0, s88

.LBB0_1354:
	s_andn2_b64 vcc, exec, s[88:89]
	s_cbranch_vccnz .LBB0_1356
	s_xor_b32 s83, s96, 1
	s_mul_i32 s88, s83, 0x3000
	s_add_i32 s88, s88, s93
	s_mov_b32 s89, m0
	s_mov_b32 m0, s88
	s_nop 0
	global_load_lds_dwordx4 v1, s[80:81]
	s_mov_b32 m0, s89
	s_lshl_b32 s83, s83, 13
	s_add_i32 s83, s83, s94
	s_mov_b32 s88, m0
	s_mov_b32 m0, s83
	s_nop 0
	global_load_lds_dwordx4 v196, s[78:79]
	s_mov_b32 m0, s88

.LBB0_1369:
	s_and_b64 vcc, exec, s[88:89]
	s_cbranch_vccz .LBB0_1385
	s_nop 9
	ds_read_b128 v[58:61], v214 offset:2048
	ds_read_b128 v[54:57], v214 offset:6144
	ds_read_b128 v[62:65], v213 offset:2048
	ds_read_b128 v[50:53], v213 offset:6144
	s_add_i32 s67, s82, 1
	s_cmp_ge_i32 s67, s39
	s_mov_b64 s[88:89], -1
	s_cbranch_scc0 .LBB0_1374
	s_andn2_b64 vcc, exec, s[70:71]
	s_cbranch_vccnz .LBB0_1373
	s_xor_b32 s83, s96, 1
	s_mul_i32 s88, s83, 0x3000
	s_add_i32 s88, s88, s93
	s_mov_b32 s89, m0
	s_mov_b32 m0, s88
	s_nop 0
	global_load_lds_dwordx4 v1, s[74:75]
	s_mov_b32 m0, s89
	s_lshl_b32 s83, s83, 13
	s_add_i32 s83, s83, s94
	s_mov_b32 s88, m0
	s_mov_b32 m0, s83
	s_nop 0
	global_load_lds_dwordx4 v196, s[76:77]
	s_mov_b32 m0, s88

.LBB0_1386:
	s_nop 4
	v_add_u32_e32 v34, v189, v199
	v_add_u32_e32 v35, v189, v203
	ds_read_b128 v[42:45], v34
	ds_read_b128 v[38:41], v34 offset:4096
	ds_read_b128 v[46:49], v35
	ds_read_b128 v[34:37], v35 offset:4096
	s_add_i32 s67, s82, 1
	s_cmp_ge_i32 s67, s39
	s_mov_b64 s[82:83], -1
	s_cbranch_scc0 .LBB0_1390
	s_andn2_b64 vcc, exec, s[70:71]
	s_cbranch_vccnz .LBB0_1389
	s_xor_b32 s82, s96, 1
	s_mul_i32 s83, s82, 0x3000
	s_add_i32 s83, s83, s93
	s_mov_b32 s86, m0
	s_mov_b32 m0, s83
	s_nop 0
	global_load_lds_dwordx4 v1, s[74:75]
	s_mov_b32 m0, s86
	s_lshl_b32 s82, s82, 13
	s_add_i32 s82, s82, s94
	s_mov_b32 s83, m0
	s_mov_b32 m0, s82
	s_nop 0
	global_load_lds_dwordx4 v196, s[76:77]
	s_mov_b32 m0, s83

.LBB0_1390:
	s_andn2_b64 vcc, exec, s[82:83]
	s_cbranch_vccnz .LBB0_1392
	s_xor_b32 s82, s96, 1
	s_mul_i32 s83, s82, 0x3000
	s_add_i32 s83, s83, s93
	s_mov_b32 s86, m0
	s_mov_b32 m0, s83
	s_nop 0
	global_load_lds_dwordx4 v1, s[80:81]
	s_mov_b32 m0, s86
	s_lshl_b32 s82, s82, 13
	s_add_i32 s82, s82, s94
	s_mov_b32 s83, m0
	s_mov_b32 m0, s82
	s_nop 0
	global_load_lds_dwordx4 v196, s[78:79]
	s_mov_b32 m0, s83

.LBB0_1548:
	s_or_b64 exec, exec, s[6:7]
	s_mov_b64 s[6:7], exec
	v_mbcnt_lo_u32_b32 v1, s6, 0
	v_mbcnt_hi_u32_b32 v1, s7, v1
	v_cmp_eq_u32_e32 vcc, 0, v1
	s_waitcnt vmcnt(0)
	s_and_saveexec_b64 s[8:9], vcc
	s_cbranch_execz .LBB0_1550
	s_bcnt1_i32_b64 s6, s[6:7]
	v_mov_b32_e32 v1, 0x2000
	v_mov_b32_e32 v2, s6
	global_atomic_add v1, v2, s[4:5] offset:1024

.LBB0_1588:
	s_andn2_saveexec_b64 s[6:7], s[6:7]
	s_cbranch_execz .LBB0_1592
	s_mov_b64 s[6:7], exec
	s_waitcnt vmcnt(0)
	v_mbcnt_lo_u32_b32 v1, s6, 0
	v_mbcnt_hi_u32_b32 v1, s7, v1
	v_cmp_eq_u32_e32 vcc, 0, v1
	s_and_saveexec_b64 s[8:9], vcc
	s_cbranch_execz .LBB0_1591
	s_bcnt1_i32_b64 s6, s[6:7]
	v_mov_b32_e32 v1, 0x2000
	v_mov_b32_e32 v2, s6
	global_atomic_add v1, v2, s[4:5] offset:1024

.LBB0_1705:
	s_mov_b64 s[0:1], exec
	s_waitcnt lgkmcnt(0)
	v_mbcnt_lo_u32_b32 v1, s0, 0
	v_mbcnt_hi_u32_b32 v1, s1, v1
	v_cmp_eq_u32_e32 vcc, 0, v1
	s_waitcnt vmcnt(0)
	s_and_saveexec_b64 s[10:11], vcc
	s_cbranch_execz .LBB0_1707
	s_bcnt1_i32_b64 s0, s[0:1]
	v_mov_b32_e32 v1, 0x2000
	v_mov_b32_e32 v2, s0
	global_atomic_add v1, v2, s[8:9] offset:1024
